# v23 + layer-0 proj phase: the 40 leftover mem-k/v tiles go to blocks whose third tile was a short mem-k/v tile (no 4th round)
# speedup vs baseline: 1.0018x; 1.0018x over previous
; DEVI int xcd_first_tile() { return (blockIdx.x & 7) * (gridDim.x >> 3) + (blockIdx.x >> 3); }
; DEVI void run_phase(const Params& p, int ph, char* smem) {
;     ...
;       for (int t = xcd_first_tile(); t < n1 + n2; t += xcd_tile_step()) {
;         if (t < n1) { int mt_, nt_; tile_coords(t, 66, 20, mt_, nt_); gemm_tile256<EPI_BF16>(p, xb, 1024, Bt, 1024, mt_ * 256, nt_ * 128, proj, DIN, smem); }
;         else {
;           const int t2 = t - n1;
;           gemm_tile<EPI_MEMKV>(p, (const u16*)(p.ws + WS_MEMP), 1024, (const u16*)(p.ws + WS_WKV), 1024, (t2 % 16) * 128, (t2 / 16) * 128, l, nullptr, 0, smem);
;         }
;       }
.LBB0_886:
	v_readlane_b32 s36, v250, 1
	v_readlane_b32 s2, v254, 37
	v_readlane_b32 s42, v250, 7
	s_add_i32 s13, s13, s2
	v_readlane_b32 s2, v254, 47
	s_add_i32 s14, s14, s42
	s_add_i32 s12, s12, s2
	s_cmpk_lg_u32 s0, 0x628
	s_cbranch_scc1 .Lmk_std
	s_cmpk_lg_u32 s42, 0x200
	s_cbranch_scc1 .Lmk_std
	s_sub_i32 s2, s14, 0x600
	s_cmpk_lt_u32 s2, 0x28
	s_cbranch_scc0 .Lmk_b
	s_movk_i32 s14, 0x4000
	s_branch .Lmk_std
.Lmk_b:
	s_sub_i32 s2, s14, 0x728
	s_cmpk_lt_u32 s2, 0x28
	s_cbranch_scc0 .Lmk_std
	s_add_i32 s14, s2, 0x600
	s_sub_i32 s2, s14, 0x528
	s_lshl_b32 s13, s2, 7
	s_lshl_b32 s12, s2, 3
.Lmk_std:
	s_cmp_ge_i32 s14, s0
	v_readlane_b32 s37, v250, 2
	v_readlane_b32 s38, v250, 3
	v_readlane_b32 s39, v250, 4
	v_readlane_b32 s40, v250, 5
	v_readlane_b32 s41, v250, 6
	v_readlane_b32 s43, v250, 8
	s_cbranch_scc1 .LBB0_917
